# grid barrier: per-XCD generation bump removed (all workgroups poll the top-level generation)
# speedup vs baseline: 1.0510x; 1.0026x over previous
.LBB0_9:
	s_or_b64 exec, exec, s[6:7]
	v_readlane_b32 s6, v253, 26
	v_readlane_b32 s7, v253, 27
	s_waitcnt vmcnt(0)
	buffer_inv sc1
	s_nop 2
	s_waitcnt vmcnt(0)
